# token-mixer phases run at equal wave priority; static raise of waves 0-3 restored for the GEMM phases
# baseline (speedup 1.0000x reference)
.LBB0_461:
	s_or_b64 exec, exec, s[0:1]
	s_add_u32 s48, s64, 0xe200000
	s_addc_u32 s49, s65, 0
	v_mov_b32_e32 v2, v181
	s_cmpk_lt_i32 s2, 0x200
	s_waitcnt lgkmcnt(0)
	s_setprio 0
	s_barrier
	s_cselect_b64 s[78:79], -1, 0
	s_cmpk_gt_i32 s2, 0x1ff
	v_readfirstlane_b32 s6, v2
	s_cbranch_scc1 .LBB0_491
	s_ashr_i32 s0, s2, 7
	s_and_b32 s7, s2, 64
	s_mul_hi_i32 s1, s0, 0xc00000
	s_mul_i32 s0, s0, 0xc00000
	s_add_u32 s0, s76, s0
	s_addc_u32 s1, s77, s1
	s_lshl_b32 s4, s2, 7
	s_and_b32 s8, s4, 0x1f80
	v_lshlrev_b32_e32 v18, 3, v2
	s_addk_i32 s8, 0xff80
	v_and_b32_e32 v0, 56, v18
	v_mov_b32_e32 v80, 0
	v_ashrrev_i32_e32 v154, 3, v2
	v_lshlrev_b32_e32 v144, 1, v0
	v_mov_b32_e32 v145, v80
	v_add_u32_e32 v3, s8, v154
	v_lshl_add_u64 v[0:1], s[0:1], 0, v[144:145]
	v_cmp_lt_i32_e32 vcc, -1, v3
	v_mov_b32_e32 v84, 0
	v_mov_b32_e32 v85, 0
	v_mov_b32_e32 v86, 0
	v_mov_b32_e32 v87, 0
	v_mov_b32_e32 v88, 0
	v_mov_b32_e32 v89, 0
	v_mov_b32_e32 v90, 0
	v_mov_b32_e32 v91, 0
	s_and_saveexec_b64 s[0:1], vcc
	s_cbranch_execz .LBB0_464
	s_movk_i32 s4, 0x600
	v_mad_u64_u32 v[4:5], s[4:5], v3, s4, v[0:1]
	s_lshl_b32 s4, s7, 1
	s_mov_b32 s5, 0
	v_lshl_add_u64 v[4:5], v[4:5], 0, s[4:5]
	global_load_dwordx4 v[88:91], v[4:5], off offset:1024
	global_load_dwordx4 v[84:87], v[4:5], off offset:1280

.LBB0_598:
	s_or_b64 exec, exec, s[0:1]
	s_waitcnt vmcnt(0)
	v_mov_b32_e32 v8, v181
	s_waitcnt lgkmcnt(0)
	v_cndmask_b32_e64 v0, 0, 1, s[78:79]
	v_cmp_gt_u32_e32 vcc, 0x100, v181
	s_cbranch_vccz .Lp2_skip0
	s_setprio 1
.Lp2_skip0:
	s_barrier
	v_cmp_ne_u32_e64 s[70:71], 1, v0
	s_andn2_b64 vcc, exec, s[78:79]
	v_readfirstlane_b32 s4, v8
	s_cbranch_vccnz .LBB0_604
	s_lshr_b32 s0, s3, 29
	s_add_i32 s5, s2, s0
	s_and_b32 s0, s5, -8
	s_sub_i32 s6, s2, s0
	s_cmp_gt_i32 s6, -1
	s_cbranch_scc0 .LBB0_601
	s_lshl_b32 s7, s6, 6
	s_cbranch_execz .LBB0_602
	s_branch .LBB0_603

.LBB0_1096:
	s_or_b64 exec, exec, s[0:1]
	s_add_u32 s50, s64, 0x16200000
	s_addc_u32 s51, s65, 0
	s_add_u32 s52, s64, 0x1c200000
	s_addc_u32 s53, s65, 0
	v_mov_b32_e32 v3, v181
	s_waitcnt lgkmcnt(0)
	s_setprio 0
	s_barrier
	s_cmpk_gt_i32 s2, 0xbff
	v_readfirstlane_b32 s8, v3
	s_cbranch_scc1 .LBB0_1129
	s_ashr_i32 s33, s8, 8
	s_lshl_b32 s78, s2, 1
	s_add_i32 s0, s33, s78
	s_bfe_u32 s1, s0, 0x20009
	s_and_b32 s12, s0, 0x1c0
	s_and_b32 s4, s0, 63
	s_ashr_i32 s0, s0, 10
	s_and_b32 s9, s0, -2
	s_bfm_b32 s0, s9, 0
	s_and_b32 s10, s0, s4
	s_lshr_b32 s0, s4, s9
	s_mul_i32 s4, s1, 0x2800000
	s_add_u32 s4, s76, s4
	s_addc_u32 s5, s77, 0
	s_lshl_b32 s11, s0, 7
	v_lshlrev_b32_e32 v4, 3, v3
	s_addk_i32 s11, 0xff80
	v_and_b32_e32 v0, 56, v4
	v_mov_b32_e32 v80, 0
	v_lshlrev_b32_e32 v160, 1, v0
	v_mov_b32_e32 v161, v80
	s_cmp_lg_u32 s0, 0
	s_mov_b32 s1, 0
	v_lshl_add_u64 v[0:1], s[4:5], 0, v[160:161]
	s_cselect_b64 s[4:5], -1, 0
	s_cmp_eq_u32 s0, 0
	v_bfe_u32 v167, v3, 3, 5
	s_cbranch_scc1 .LBB0_1099
	v_or_b32_e32 v2, s11, v167
	v_lshlrev_b32_e32 v2, s9, v2
	v_add_u32_e32 v2, s10, v2
	s_movk_i32 s0, 0x1400
	v_mad_i64_i32 v[6:7], s[6:7], v2, s0, v[0:1]
	s_lshl_b32 s0, s12, 1
	v_lshl_add_u64 v[6:7], v[6:7], 0, s[0:1]
	global_load_dwordx4 v[80:83], v[6:7], off offset:1024
	global_load_dwordx4 v[84:87], v[6:7], off offset:2048
	s_branch .LBB0_1100

.LBB0_1272:
	s_or_b64 exec, exec, s[0:1]
	v_mov_b32_e32 v8, v181
	s_waitcnt lgkmcnt(0)
	v_cmp_gt_u32_e32 vcc, 0x100, v181
	s_cbranch_vccz .Lp2_skip1
	s_setprio 1
.Lp2_skip1:
	s_barrier
	s_and_b64 vcc, exec, s[70:71]
	v_readfirstlane_b32 s4, v8
	s_cbranch_vccnz .LBB0_1278
	s_lshr_b32 s0, s3, 29
	s_add_i32 s5, s2, s0
	s_and_b32 s0, s5, -8
	s_sub_i32 s6, s2, s0
	s_cmp_gt_i32 s6, -1
	s_cbranch_scc0 .LBB0_1275
	s_lshl_b32 s7, s6, 6
	s_cbranch_execz .LBB0_1276
	s_branch .LBB0_1277
